# grid barrier: all workgroups wait on the cross-XCD release word (TOPGEN), per-XCD release hop removed
# speedup vs baseline: 1.0158x; 1.0038x over previous
; __device__ __forceinline__ unsigned xb_ld(unsigned* p)              { return __hip_atomic_load(p, __ATOMIC_RELAXED, __HIP_MEMORY_SCOPE_AGENT); }
; __device__ __forceinline__ unsigned xb_add(unsigned* p, unsigned v) { return __hip_atomic_fetch_add(p, v, __ATOMIC_RELAXED, __HIP_MEMORY_SCOPE_AGENT); }
; #define XB_SPIN(cond, bar) do { unsigned _sp = 0; while (cond) { __builtin_amdgcn_s_sleep(1); \
;     if ((++_sp & 255u) == 0u) { if (xb_ld(&(bar)[XB_TMO])) break; if (_sp > XB_SPIN_CAP) { atomicAdd(&(bar)[XB_TMO], 1u); break; } } } } while (0)
; __device__ __forceinline__ void xcd_barrier(const XcdBarrier& b) {
;     ...
;             const unsigned og = xb_add(&bar[XB_TOP], 1u);
;             const unsigned tg = og / nx;
;             if (og + 1u == (tg + 1u) * nx) xb_add(&bar[XB_TOPGEN], 1u);
;             else XB_SPIN(xb_ld(&bar[XB_TOPGEN]) == tg, bar);
;             __builtin_amdgcn_fence(__ATOMIC_ACQUIRE, "agent");
;             xb_add(&bar[XB_XGEN(b.x)], 1u);
;             asm volatile("s_waitcnt vmcnt(0)" ::: "memory");
.LBB0_12:
	s_or_b64 exec, exec, s[8:9]
	v_mov_b32_e32 v0, 0x2000
	s_waitcnt vmcnt(0)
	buffer_inv sc1
	s_waitcnt vmcnt(0)

; __device__ __forceinline__ unsigned xb_ld(unsigned* p)              { return __hip_atomic_load(p, __ATOMIC_RELAXED, __HIP_MEMORY_SCOPE_AGENT); }
; __device__ __forceinline__ unsigned xb_add(unsigned* p, unsigned v) { return __hip_atomic_fetch_add(p, v, __ATOMIC_RELAXED, __HIP_MEMORY_SCOPE_AGENT); }
; #define XB_SPIN(cond, bar) do { unsigned _sp = 0; while (cond) { __builtin_amdgcn_s_sleep(1); \
;     if ((++_sp & 255u) == 0u) { if (xb_ld(&(bar)[XB_TMO])) break; if (_sp > XB_SPIN_CAP) { atomicAdd(&(bar)[XB_TMO], 1u); break; } } } } while (0)
; __device__ __forceinline__ void xcd_barrier(const XcdBarrier& b) {
;     ...
;         unsigned nloc = b.st[0], nx = b.st[1];
;         if (nloc == 0u) { xcd_barrier_complete(bar, b.x, nloc, nx); b.st[0] = nloc; b.st[1] = nx; }
;         const unsigned old = xb_add(&bar[XB_XSUB(b.x)], 1u);
;         const unsigned gen = old / nloc;
;         if (old + 1u == (gen + 1u) * nloc) {
;             __builtin_amdgcn_fence(__ATOMIC_RELEASE, "agent");
;             asm volatile("s_waitcnt vmcnt(0)" ::: "memory");
;             const unsigned og = xb_add(&bar[XB_TOP], 1u);
;             const unsigned tg = og / nx;
;             if (og + 1u == (tg + 1u) * nx) xb_add(&bar[XB_TOPGEN], 1u);
;             else XB_SPIN(xb_ld(&bar[XB_TOPGEN]) == tg, bar);
;             __builtin_amdgcn_fence(__ATOMIC_ACQUIRE, "agent");
;             xb_add(&bar[XB_XGEN(b.x)], 1u);
;             asm volatile("s_waitcnt vmcnt(0)" ::: "memory");
;         } else {
;             XB_SPIN(xb_ld(&bar[XB_XGEN(b.x)]) == gen, bar);
;             __builtin_amdgcn_fence(__ATOMIC_ACQUIRE, "agent");
;             asm volatile("s_waitcnt vmcnt(0)" ::: "memory");
;         }
.LBB0_510:
	v_readlane_b32 s6, v254, 40
	s_lshl_b32 s84, s6, 6
	s_lshl_b64 s[6:7], s[84:85], 2
	s_add_u32 s6, s90, s6
	s_addc_u32 s7, s91, s7
	v_mov_b32_e32 v0, 0x1000
	global_atomic_add v4, v0, v233, s[6:7] offset:1024 sc0
	v_cvt_f32_u32_e32 v0, v3
	v_sub_u32_e32 v5, 0, v3
	v_rcp_iflag_f32_e32 v0, v0
	s_nop 0
	v_mul_f32_e32 v0, 0x4f7ffffe, v0
	v_cvt_u32_f32_e32 v0, v0
	v_mul_lo_u32 v5, v5, v0
	v_mul_hi_u32 v5, v0, v5
	v_add_u32_e32 v0, v0, v5
	s_waitcnt vmcnt(0)
	v_mul_hi_u32 v0, v4, v0
	v_mul_lo_u32 v5, v0, v3
	v_sub_u32_e32 v5, v4, v5
	v_add_u32_e32 v6, 1, v0
	v_cmp_ge_u32_e32 vcc, v5, v3
	v_add_u32_e32 v4, 1, v4
	s_nop 0
	v_cndmask_b32_e32 v0, v0, v6, vcc
	v_sub_u32_e32 v6, v5, v3
	v_cndmask_b32_e32 v5, v5, v6, vcc
	v_add_u32_e32 v6, 1, v0
	v_cmp_ge_u32_e32 vcc, v5, v3
	s_nop 1
	v_cndmask_b32_e32 v0, v0, v6, vcc
	v_mul_lo_u32 v5, v3, v0
	v_add_u32_e32 v3, v5, v3
	v_cmp_ne_u32_e32 vcc, v4, v3
	s_and_saveexec_b64 s[8:9], vcc
	s_xor_b64 s[8:9], exec, s[8:9]
	s_cbranch_execz .LBB0_524
	s_waitcnt lgkmcnt(0)
	v_readlane_b32 s12, v253, 15
	v_readlane_b32 s13, v253, 16
	s_nop 4
	global_load_dword v2, v1, s[12:13] sc1
	s_waitcnt vmcnt(0)
	v_cmp_eq_u32_e32 vcc, v2, v0
	s_and_saveexec_b64 s[10:11], vcc
	s_cbranch_execz .LBB0_523
	s_mov_b32 s24, 1
	s_mov_b64 s[14:15], 0
	s_branch .LBB0_514
